# scan operand sharing through LDS applied to the phase-4 scan as well (each wave loads a quarter of the shared P/Q tiles)
# speedup vs baseline: 1.0524x; 1.0151x over previous
.LBB0_734:
	v_lshrrev_b32_e32 v234, 6, v218
	s_nop 1
	v_readfirstlane_b32 s98, v234
	v_and_b32_e32 v234, 63, v218
	v_lshlrev_b32_e32 v234, 4, v234
	s_mul_i32 s12, s2, 0xc0000
	v_and_b32_e32 v219, 63, v218
	v_lshrrev_b32_e32 v220, 6, v218
	s_lshl_b32 s3, s2, 6
	s_or_b32 s5, s12, 0x3000
	v_readlane_b32 s16, v242, 1
	v_lshl_or_b32 v104, v220, 7, v219
	v_readlane_b32 s17, v242, 2
	s_add_u32 s6, s16, s5
	v_lshlrev_b32_e32 v0, 6, v219
	v_lshrrev_b32_e32 v1, 1, v218
	v_mov_b32_e32 v165, 0
	s_addc_u32 s7, s17, 0
	v_lshlrev_b32_e32 v164, 3, v104
	v_and_b32_e32 v96, 0x3c0, v0
	v_and_b32_e32 v98, 24, v1
	v_or_b32_e32 v100, 0xc00, v0
	v_lshl_add_u64 v[0:1], s[6:7], 0, v[164:165]
	s_mov_b64 s[0:1], 0x2000
	s_movk_i32 s4, 0x2000
	s_add_u32 s8, s80, s5
	v_lshl_or_b32 v102, v220, 8, v219
	v_lshl_add_u64 v[2:3], v[0:1], 0, s[0:1]
	v_add_co_u32_e32 v0, vcc, s4, v0
	s_addc_u32 s9, s81, 0
	s_nop 0
	v_addc_co_u32_e32 v1, vcc, 0, v1, vcc
	v_lshlrev_b32_e32 v42, 3, v102
	s_add_u32 s10, s16, s12
	v_lshlrev_b32_e32 v32, 1, v98
	v_mov_b32_e32 v33, v165
	s_addc_u32 s11, s17, 0
	global_load_dwordx2 v[166:167], v42, s[6:7] offset:1536
	global_load_dwordx2 v[172:173], v42, s[10:11] offset:512
	global_load_dwordx2 v[180:181], v42, s[10:11]
	global_load_dwordx2 v[170:171], v42, s[6:7] offset:1024
	global_load_dwordx2 v[198:199], v[2:3], off offset:512
	global_load_dwordx2 v[202:203], v[0:1], off
	global_load_dwordx2 v[174:175], v42, s[6:7] offset:512
	global_load_dwordx2 v[184:185], v42, s[6:7]
	v_lshlrev_b32_e32 v34, 1, v96
	v_mov_b32_e32 v35, v165
	v_lshl_add_u64 v[0:1], s[8:9], 0, v[32:33]
	v_lshl_add_u64 v[28:29], v[0:1], 0, v[34:35]
	v_add_co_u32_e32 v4, vcc, s4, v28
	s_movk_i32 s5, 0x1000
	s_nop 0
	v_addc_co_u32_e32 v5, vcc, 0, v29, vcc
	v_add_co_u32_e32 v12, vcc, s5, v28
	s_add_u32 s6, s80, s12
	s_nop 0
	v_addc_co_u32_e32 v13, vcc, 0, v29, vcc
	v_lshl_add_u64 v[38:39], s[10:11], 0, v[164:165]
	s_addc_u32 s7, s81, 0
	v_lshl_add_u64 v[2:3], v[28:29], 0, s[0:1]
	v_lshlrev_b32_e32 v36, 1, v100
	v_mov_b32_e32 v37, v165
	v_lshl_add_u64 v[40:41], v[38:39], 0, s[0:1]
	v_add_co_u32_e32 v38, vcc, s4, v38
	v_lshl_add_u64 v[32:33], s[6:7], 0, v[32:33]
	s_cmp_lg_u32 s98, 2
	s_cbranch_scc1 .Lss_g1001
	global_load_dwordx4 v[56:59], v[2:3], off offset:2048
.Lss_g1001:
	s_cmp_lg_u32 s98, 3
	s_cbranch_scc1 .Lss_g1002
	global_load_dwordx4 v[72:75], v[2:3], off offset:64
.Lss_g1002:
	s_cmp_lg_u32 s98, 3
	s_cbranch_scc1 .Lss_g1003
	global_load_dwordx4 v[60:63], v[2:3], off offset:2112

.Lss_g1004:
	v_lshl_add_u64 v[4:5], v[0:1], 0, v[36:37]
	v_addc_co_u32_e32 v39, vcc, 0, v39, vcc
	v_lshl_add_u64 v[68:69], v[32:33], 0, v[34:35]
	s_cmp_lg_u32 s98, 0
	s_cbranch_scc1 .Lss_g1005
	global_load_dwordx4 v[0:3], v[4:5], off offset:64
.Lss_g1005:
	s_nop 0
	s_cmp_lg_u32 s98, 0
	s_cbranch_scc1 .Lss_g1006
	global_load_dwordx4 v[4:7], v[4:5], off

.Lss_g1007:
	s_nop 0
	s_cmp_lg_u32 s98, 1
	s_cbranch_scc1 .Lss_g1008
	global_load_dwordx4 v[12:15], v[12:13], off
.Lss_g1008:
	s_nop 0
	s_cmp_lg_u32 s98, 1
	s_cbranch_scc1 .Lss_g1009
	global_load_dwordx4 v[16:19], v[28:29], off offset:2112
.Lss_g1009:
	s_cmp_lg_u32 s98, 1
	s_cbranch_scc1 .Lss_g1010
	global_load_dwordx4 v[20:23], v[28:29], off offset:2048

.Lss_g1012:
	s_nop 0
	global_load_dwordx2 v[200:201], v[40:41], off offset:512
	global_load_dwordx2 v[204:205], v[38:39], off
	global_load_dwordx2 v[188:189], v42, s[10:11] offset:1536
	global_load_dwordx2 v[196:197], v42, s[10:11] offset:1024
	v_add_co_u32_e32 v38, vcc, s4, v68
	v_lshl_add_u64 v[34:35], v[68:69], 0, s[0:1]
	s_nop 0
	v_addc_co_u32_e32 v39, vcc, 0, v69, vcc
	v_add_co_u32_e32 v44, vcc, s5, v68
	v_lshl_add_u64 v[36:37], v[32:33], 0, v[36:37]
	s_nop 0
	v_addc_co_u32_e32 v45, vcc, 0, v69, vcc
	s_cmp_lg_u32 s98, 2
	s_cbranch_scc1 .Lss_g1013
	global_load_dwordx4 v[80:83], v[34:35], off offset:2048

.Lss_g1016:
	s_nop 0
	s_cmp_lg_u32 s98, 0
	s_cbranch_scc1 .Lss_g1017
	global_load_dwordx4 v[32:35], v[36:37], off offset:64
.Lss_g1017:
	s_nop 0
	s_cmp_lg_u32 s98, 0
	s_cbranch_scc1 .Lss_g1018
	global_load_dwordx4 v[36:39], v[36:37], off
.Lss_g1018:
	s_nop 0
	s_cmp_lg_u32 s98, 0
	s_cbranch_scc1 .Lss_g1019
	global_load_dwordx4 v[40:43], v[44:45], off offset:64
.Lss_g1019:
	s_nop 0
	s_cmp_lg_u32 s98, 1
	s_cbranch_scc1 .Lss_g1020
	global_load_dwordx4 v[44:47], v[44:45], off
.Lss_g1020:
	s_nop 0
	s_cmp_lg_u32 s98, 1
	s_cbranch_scc1 .Lss_g1021
	global_load_dwordx4 v[48:51], v[68:69], off offset:2112
.Lss_g1021:
	s_cmp_lg_u32 s98, 1
	s_cbranch_scc1 .Lss_g1022
	global_load_dwordx4 v[52:55], v[68:69], off offset:2048
.Lss_g1022:
	s_cmp_lg_u32 s98, 2
	s_cbranch_scc1 .Lss_g1023
	global_load_dwordx4 v[64:67], v[68:69], off offset:64
.Lss_g1023:
	s_nop 0
	s_cmp_lg_u32 s98, 2
	s_cbranch_scc1 .Lss_g1024
	global_load_dwordx4 v[68:71], v[68:69], off
.Lss_g1024:
	v_bfe_u32 v101, v218, 4, 2
	v_and_b32_e32 v97, 15, v218
	v_mul_u32_u24_e32 v99, 0x1100, v220
	v_mul_u32_u24_e32 v103, 0x110, v101
	v_lshl_or_b32 v105, v97, 2, v99
	v_lshlrev_b32_e32 v103, 2, v103
	v_add_u32_e32 v221, v105, v103
	v_lshlrev_b32_e32 v105, 2, v219
	s_movk_i32 s7, 0xc0
	v_or3_b32 v99, v105, v99, s7
	s_lshl_b32 s7, s2, 8
	v_mov_b32_e32 v105, 0x380f
	v_bitop3_b32 v105, s7, v105, v218 bitop3:0xc8
	s_and_b32 s7, s2, 7
	s_mov_b32 s9, 0
	s_lshl_b32 s8, s7, 7
	v_lshlrev_b32_e32 v106, 5, v220
	v_mov_b32_e32 v107, v165
	s_lshl_b32 s7, s2, 18
	s_movk_i32 s6, 0x1100
	v_add_u32_e32 v222, v99, v103
	v_mul_u32_u24_e32 v99, 0x110, v97
	v_lshl_add_u64 v[106:107], s[8:9], 0, v[106:107]
	s_and_b32 s7, s7, 0xe00000
	v_mad_u32_u24 v99, v220, s6, v99
	v_lshlrev_b32_e32 v103, 5, v101
	v_lshlrev_b32_e32 v168, 10, v105
	v_lshl_or_b32 v106, v101, 3, v106
	v_lshl_or_b32 v97, v97, 10, s7
	s_or_b32 s6, s3, 4
	v_or_b32_e32 v164, 0x8000, v168
	v_lshl_add_u64 v[176:177], s[16:17], 0, v[106:107]
	v_or_b32_e32 v178, 0x4000, v168
	v_mov_b32_e32 v179, v165
	v_mov_b32_e32 v169, v165
	v_or_b32_e32 v182, 0x10000, v97
	v_mov_b32_e32 v183, v165
	s_mov_b32 s7, -3
	v_lshlrev_b32_e32 v186, 1, v98
	v_mov_b32_e32 v187, v165
	v_lshlrev_b32_e32 v190, 1, v96
	v_mov_b32_e32 v191, v165
	v_lshlrev_b32_e32 v192, 1, v100
	v_mov_b32_e32 v193, v165
	v_lshlrev_b32_e32 v223, 3, v102
	v_lshlrev_b32_e32 v194, 3, v104
	v_mov_b32_e32 v195, v165
	v_add_u32_e32 v224, v99, v103
	s_mov_b32 s8, 0x3000000
	s_mov_b32 s9, 0x3004000
	v_mov_b32_e32 v144, v165
	v_mov_b32_e32 v145, v165
	v_mov_b32_e32 v146, v165
	v_mov_b32_e32 v147, v165
	v_mov_b32_e32 v148, v165
	v_mov_b32_e32 v149, v165
	v_mov_b32_e32 v150, v165
	v_mov_b32_e32 v151, v165
	v_mov_b32_e32 v152, v165
	v_mov_b32_e32 v153, v165
	v_mov_b32_e32 v154, v165
	v_mov_b32_e32 v155, v165
	v_mov_b32_e32 v156, v165
	v_mov_b32_e32 v157, v165
	v_mov_b32_e32 v158, v165
	v_mov_b32_e32 v159, v165
	v_readlane_b32 s18, v242, 3
	v_readlane_b32 s19, v242, 4
	v_readlane_b32 s20, v242, 5
	v_readlane_b32 s21, v242, 6
	v_readlane_b32 s22, v242, 7
	v_readlane_b32 s23, v242, 8
	v_readlane_b32 s24, v242, 9
	v_readlane_b32 s25, v242, 10
	v_readlane_b32 s26, v242, 11
	v_readlane_b32 s27, v242, 12
	v_readlane_b32 s28, v242, 13
	v_readlane_b32 s29, v242, 14
	v_readlane_b32 s30, v242, 15
	v_readlane_b32 s31, v242, 16
	s_waitcnt vmcnt(0)
	s_branch .LBB0_736

.LBB0_736:
	s_mov_b32 s10, s7
	s_add_i32 s11, s10, 5
	s_min_u32 s11, s11, 31
	s_or_b32 s11, s11, s3
	s_add_i32 s7, s7, 3
	s_mulk_i32 s11, 0x3000
	s_add_u32 s12, s80, s11
	s_addc_u32 s13, s81, 0
	s_waitcnt vmcnt(63)
	v_lshl_add_u64 v[96:97], s[12:13], 0, v[186:187]
	s_waitcnt vmcnt(63)
	v_lshl_add_u64 v[128:129], v[96:97], 0, v[190:191]
	v_add_co_u32_e32 v98, vcc, s5, v128
	v_readlane_b32 s16, v242, 1
	s_nop 0
	v_addc_co_u32_e32 v99, vcc, 0, v129, vcc
	v_readlane_b32 s17, v242, 2
	s_add_u32 s12, s16, s11
	v_add_co_u32_e32 v130, vcc, s4, v128
	s_addc_u32 s13, s17, 0
	s_nop 0
	v_addc_co_u32_e32 v131, vcc, 0, v129, vcc
	v_lshl_add_u64 v[160:161], s[12:13], 0, v[194:195]
	v_lshl_add_u64 v[162:163], v[160:161], 0, s[0:1]
	v_add_co_u32_e32 v160, vcc, s4, v160
	s_cmp_lg_u32 s98, 2
	s_cbranch_scc1 .Lss_g1025
	global_load_dwordx4 v[124:127], v[128:129], off
.Lss_g1025:
	s_cmp_lg_u32 s98, 2
	s_cbranch_scc1 .Lss_g1026
	global_load_dwordx4 v[120:123], v[128:129], off offset:64
.Lss_g1026:
	s_cmp_lg_u32 s98, 1
	s_cbranch_scc1 .Lss_g1027
	global_load_dwordx4 v[116:119], v[128:129], off offset:2048
.Lss_g1027:
	s_cmp_lg_u32 s98, 1
	s_cbranch_scc1 .Lss_g1028
	global_load_dwordx4 v[112:115], v[128:129], off offset:2112
.Lss_g1028:
	v_lshl_add_u64 v[96:97], v[96:97], 0, v[192:193]
	v_lshl_add_u64 v[128:129], v[128:129], 0, s[0:1]
	v_addc_co_u32_e32 v161, vcc, 0, v161, vcc
	s_cmp_lg_u32 s98, 1
	s_cbranch_scc1 .Lss_g1029
	global_load_dwordx4 v[108:111], v[130:131], off offset:-4096
.Lss_g1029:
	s_cmp_lg_u32 s98, 0
	s_cbranch_scc1 .Lss_g1030
	global_load_dwordx4 v[100:103], v[98:99], off offset:64
.Lss_g1030:
	s_cmp_lg_u32 s98, 0
	s_cbranch_scc1 .Lss_g1031
	global_load_dwordx4 v[104:107], v[96:97], off
.Lss_g1031:
	s_nop 0
	s_cmp_lg_u32 s98, 0
	s_cbranch_scc1 .Lss_g1032
	global_load_dwordx4 v[96:99], v[96:97], off offset:64
.Lss_g1032:
	s_nop 0
	s_cmp_lg_u32 s98, 3
	s_cbranch_scc1 .Lss_g1033
	global_load_dwordx4 v[140:143], v[130:131], off
.Lss_g1033:
	s_cmp_lg_u32 s98, 3
	s_cbranch_scc1 .Lss_g1034
	global_load_dwordx4 v[136:139], v[128:129], off offset:64
.Lss_g1034:
	s_cmp_lg_u32 s98, 3
	s_cbranch_scc1 .Lss_g1035
	global_load_dwordx4 v[132:135], v[128:129], off offset:2048
.Lss_g1035:
	s_nop 0
	s_cmp_lg_u32 s98, 2
	s_cbranch_scc1 .Lss_g1036
	global_load_dwordx4 v[128:131], v[128:129], off offset:2112
.Lss_g1036:
	s_nop 0
	global_load_dwordx2 v[212:213], v223, s[12:13]
	global_load_dwordx2 v[210:211], v223, s[12:13] offset:512
	global_load_dwordx2 v[208:209], v223, s[12:13] offset:1024
	global_load_dwordx2 v[206:207], v223, s[12:13] offset:1536
	global_load_dwordx2 v[216:217], v[160:161], off
	global_load_dwordx2 v[214:215], v[162:163], off offset:512
	s_waitcnt vmcnt(22)
	s_cmp_lg_u32 s98, 0
	s_cbranch_scc1 .Lss_x1061_1
	ds_write_b128 v234, v[32:35] offset:32768
	ds_write_b128 v234, v[36:39] offset:33792
	ds_write_b128 v234, v[40:43] offset:34816
	s_branch .Lss_x1061_d
.Lss_x1061_1:
	s_cmp_lg_u32 s98, 1
	s_cbranch_scc1 .Lss_x1061_2
	ds_write_b128 v234, v[44:47] offset:35840
	ds_write_b128 v234, v[48:51] offset:36864
	ds_write_b128 v234, v[52:55] offset:37888
	s_branch .Lss_x1061_d
.Lss_x1061_2:
	s_cmp_lg_u32 s98, 2
	s_cbranch_scc1 .Lss_x1061_3
	ds_write_b128 v234, v[64:67] offset:38912
	ds_write_b128 v234, v[68:71] offset:39936
	ds_write_b128 v234, v[80:83] offset:40960
	s_branch .Lss_x1061_d

.Lss_x1061_d:
	s_waitcnt lgkmcnt(0)
	s_barrier
	ds_read_b128 v[32:35], v234 offset:32768
	ds_read_b128 v[36:39], v234 offset:33792
	ds_read_b128 v[40:43], v234 offset:34816
	ds_read_b128 v[44:47], v234 offset:35840
	ds_read_b128 v[48:51], v234 offset:36864
	ds_read_b128 v[52:55], v234 offset:37888
	ds_read_b128 v[64:67], v234 offset:38912
	ds_read_b128 v[68:71], v234 offset:39936
	ds_read_b128 v[80:83], v234 offset:40960
	ds_read_b128 v[84:87], v234 offset:41984
	ds_read_b128 v[88:91], v234 offset:43008
	ds_read_b128 v[92:95], v234 offset:44032
	s_waitcnt lgkmcnt(0)
	ds_write2_b32 v221, v144, v148 offset1:16
	ds_write2_b32 v221, v146, v150 offset0:136 offset1:152
	ds_write2_b32 v221, v152, v145 offset0:32 offset1:68
	ds_write2_b32 v221, v149, v153 offset0:84 offset1:100
	ds_write2_b32 v221, v154, v147 offset0:168 offset1:204
	ds_write2_b32 v221, v151, v155 offset0:220 offset1:236
	ds_write2_b32 v222, v156, v157 offset1:68
	ds_write2_b32 v222, v158, v159 offset0:136 offset1:204
	ds_read_b128 v[148:151], v224
	ds_read_b128 v[152:155], v224 offset:16
	ds_read_b128 v[160:163], v224 offset:144
	s_add_i32 s10, s10, 6
	s_min_u32 s10, s10, 31
	s_waitcnt lgkmcnt(2)
	v_cvt_pk_bf16_f32 v144, v148, v149
	v_lshlrev_b32_e32 v146, 16, v144
	v_and_b32_e32 v147, 0xffff0000, v144
	v_pk_add_f32 v[146:147], v[148:149], v[146:147] neg_lo:[0,1] neg_hi:[0,1]
	v_cvt_pk_bf16_f32 v145, v150, v151
	v_cvt_pk_bf16_f32 v148, v146, v147
	v_lshlrev_b32_e32 v146, 16, v145
	v_and_b32_e32 v147, 0xffff0000, v145
	v_pk_add_f32 v[146:147], v[150:151], v[146:147] neg_lo:[0,1] neg_hi:[0,1]
	s_or_b32 s10, s10, s3
	v_cvt_pk_bf16_f32 v149, v146, v147
	s_waitcnt lgkmcnt(1)
	v_cvt_pk_bf16_f32 v146, v152, v153
	v_lshlrev_b32_e32 v150, 16, v146
	v_and_b32_e32 v151, 0xffff0000, v146
	v_cvt_pk_bf16_f32 v147, v154, v155
	v_pk_add_f32 v[150:151], v[152:153], v[150:151] neg_lo:[0,1] neg_hi:[0,1]
	v_lshlrev_b32_e32 v152, 16, v147
	v_and_b32_e32 v153, 0xffff0000, v147
	v_pk_add_f32 v[152:153], v[154:155], v[152:153] neg_lo:[0,1] neg_hi:[0,1]
	v_cvt_pk_bf16_f32 v150, v150, v151
	v_cvt_pk_bf16_f32 v151, v152, v153
	ds_read_b128 v[152:155], v224 offset:128
	s_mul_i32 s12, s10, 0x3000
	s_add_u32 s10, s80, s12
	s_addc_u32 s11, s81, 0
	v_readlane_b32 s18, v242, 3
	s_waitcnt lgkmcnt(0)
	v_cvt_pk_bf16_f32 v156, v152, v153
	v_lshlrev_b32_e32 v158, 16, v156
	v_and_b32_e32 v159, 0xffff0000, v156
	v_cvt_pk_bf16_f32 v157, v154, v155
	v_pk_add_f32 v[152:153], v[152:153], v[158:159] neg_lo:[0,1] neg_hi:[0,1]
	v_lshlrev_b32_e32 v158, 16, v157
	v_and_b32_e32 v159, 0xffff0000, v157
	v_pk_add_f32 v[154:155], v[154:155], v[158:159] neg_lo:[0,1] neg_hi:[0,1]
	v_cvt_pk_bf16_f32 v158, v160, v161
	v_cvt_pk_bf16_f32 v152, v152, v153
	v_cvt_pk_bf16_f32 v153, v154, v155
	v_lshlrev_b32_e32 v154, 16, v158
	v_and_b32_e32 v155, 0xffff0000, v158
	v_cvt_pk_bf16_f32 v159, v162, v163
	v_pk_add_f32 v[154:155], v[160:161], v[154:155] neg_lo:[0,1] neg_hi:[0,1]
	v_lshlrev_b32_e32 v160, 16, v159
	v_and_b32_e32 v161, 0xffff0000, v159
	v_pk_add_f32 v[160:161], v[162:163], v[160:161] neg_lo:[0,1] neg_hi:[0,1]
	v_cvt_pk_bf16_f32 v154, v154, v155
	v_cvt_pk_bf16_f32 v155, v160, v161
	s_waitcnt vmcnt(63)
	v_lshlrev_b32_e32 v160, 16, v204
	v_and_b32_e32 v161, 0xffff0000, v204
	v_lshlrev_b32_e32 v162, 16, v205
	v_and_b32_e32 v163, 0xffff0000, v205
	v_readlane_b32 s19, v242, 4
	v_readlane_b32 s20, v242, 5
	s_waitcnt vmcnt(63)
	v_mfma_f32_16x16x32_bf16 v[160:163], v[144:147], v[92:95], v[160:163]
	v_readlane_b32 s21, v242, 6
	v_readlane_b32 s22, v242, 7
	v_readlane_b32 s23, v242, 8
	v_mfma_f32_16x16x32_bf16 v[92:95], v[148:151], v[92:95], v[160:163]
	v_readlane_b32 s24, v242, 9
	v_readlane_b32 s25, v242, 10
	v_readlane_b32 s26, v242, 11
	v_mfma_f32_16x16x32_bf16 v[92:95], v[156:159], v[88:91], v[92:95]
	v_readlane_b32 s27, v242, 12
	v_readlane_b32 s28, v242, 13
	v_readlane_b32 s29, v242, 14
	v_mfma_f32_16x16x32_bf16 v[88:91], v[152:155], v[88:91], v[92:95]
	v_readlane_b32 s30, v242, 15
	v_readlane_b32 s31, v242, 16
	s_nop 1
	v_lshlrev_b32_e32 v92, 16, v200
	v_and_b32_e32 v93, 0xffff0000, v200
	v_lshlrev_b32_e32 v94, 16, v201
	v_and_b32_e32 v95, 0xffff0000, v201
	s_nop 1
	v_mfma_f32_16x16x32_bf16 v[92:95], v[144:147], v[80:83], v[92:95]
	v_mfma_f32_16x16x32_bf16 v[80:83], v[148:151], v[80:83], v[92:95]
	v_mfma_f32_16x16x32_bf16 v[80:83], v[156:159], v[84:87], v[80:83]
	v_mfma_f32_16x16x32_bf16 v[80:83], v[152:155], v[84:87], v[80:83]
	v_lshlrev_b32_e32 v84, 16, v180
	v_and_b32_e32 v85, 0xffff0000, v180
	v_lshlrev_b32_e32 v86, 16, v181
	v_and_b32_e32 v87, 0xffff0000, v181
	s_waitcnt vmcnt(63)
	s_nop 0
	v_mfma_f32_16x16x32_bf16 v[84:87], v[144:147], v[68:71], v[84:87]
	v_mfma_f32_16x16x32_bf16 v[68:71], v[148:151], v[68:71], v[84:87]
	v_mfma_f32_16x16x32_bf16 v[68:71], v[156:159], v[64:67], v[68:71]
	v_mfma_f32_16x16x32_bf16 v[160:163], v[152:155], v[64:67], v[68:71]
	v_lshlrev_b32_e32 v64, 16, v172
	v_and_b32_e32 v65, 0xffff0000, v172
	v_lshlrev_b32_e32 v66, 16, v173
	v_and_b32_e32 v67, 0xffff0000, v173
	s_nop 1
	v_mfma_f32_16x16x32_bf16 v[64:67], v[144:147], v[52:55], v[64:67]
	v_mfma_f32_16x16x32_bf16 v[52:55], v[148:151], v[52:55], v[64:67]
	v_mfma_f32_16x16x32_bf16 v[52:55], v[156:159], v[48:51], v[52:55]
	v_mfma_f32_16x16x32_bf16 v[226:229], v[152:155], v[48:51], v[52:55]
	v_lshlrev_b32_e32 v48, 16, v196
	v_and_b32_e32 v49, 0xffff0000, v196
	v_lshlrev_b32_e32 v50, 16, v197
	v_and_b32_e32 v51, 0xffff0000, v197
	s_nop 1
	v_mfma_f32_16x16x32_bf16 v[48:51], v[144:147], v[44:47], v[48:51]
	v_mfma_f32_16x16x32_bf16 v[44:47], v[148:151], v[44:47], v[48:51]
	v_mfma_f32_16x16x32_bf16 v[44:47], v[156:159], v[40:43], v[44:47]
	v_mfma_f32_16x16x32_bf16 v[230:233], v[152:155], v[40:43], v[44:47]
	v_lshlrev_b32_e32 v40, 16, v188
	v_and_b32_e32 v41, 0xffff0000, v188
	v_lshlrev_b32_e32 v42, 16, v189
	v_and_b32_e32 v43, 0xffff0000, v189
	s_nop 1
	v_mfma_f32_16x16x32_bf16 v[40:43], v[144:147], v[36:39], v[40:43]
	v_mfma_f32_16x16x32_bf16 v[36:39], v[148:151], v[36:39], v[40:43]
	v_mfma_f32_16x16x32_bf16 v[36:39], v[156:159], v[32:35], v[36:39]
	v_mfma_f32_16x16x32_bf16 v[144:147], v[152:155], v[32:35], v[36:39]
	v_lshl_add_u64 v[34:35], v[176:177], 0, v[168:169]
	v_add_co_u32_e32 v34, vcc, s8, v34
	v_cvt_pk_bf16_f32 v32, v88, v89
	v_cvt_pk_bf16_f32 v33, v90, v91
	v_addc_co_u32_e32 v35, vcc, 0, v35, vcc
	global_store_dwordx2 v[34:35], v[32:33], off
	v_lshl_add_u64 v[34:35], v[176:177], 0, v[178:179]
	v_add_co_u32_e32 v34, vcc, s8, v34
	v_cvt_pk_bf16_f32 v32, v80, v81
	v_cvt_pk_bf16_f32 v33, v82, v83
	v_addc_co_u32_e32 v35, vcc, 0, v35, vcc
	global_store_dwordx2 v[34:35], v[32:33], off
	v_lshl_add_u64 v[32:33], s[10:11], 0, v[186:187]
	v_lshl_add_u64 v[80:81], v[32:33], 0, v[190:191]
	v_add_co_u32_e32 v34, vcc, s5, v80
	s_add_u32 s10, s16, s12
	s_nop 0
	v_addc_co_u32_e32 v35, vcc, 0, v81, vcc
	v_add_co_u32_e32 v82, vcc, s4, v80
	s_addc_u32 s11, s17, 0
	s_nop 0
	v_addc_co_u32_e32 v83, vcc, 0, v81, vcc
	v_lshl_add_u64 v[148:149], s[10:11], 0, v[194:195]
	v_lshl_add_u64 v[150:151], v[148:149], 0, s[0:1]
	v_add_co_u32_e32 v148, vcc, s4, v148
	v_lshl_add_u64 v[32:33], v[32:33], 0, v[192:193]
	v_lshl_add_u64 v[84:85], v[80:81], 0, s[0:1]
	v_addc_co_u32_e32 v149, vcc, 0, v149, vcc
	s_cmp_lg_u32 s98, 2
	s_cbranch_scc1 .Lss_g1037
	global_load_dwordx4 v[68:71], v[80:81], off
.Lss_g1037:
	s_cmp_lg_u32 s98, 2
	s_cbranch_scc1 .Lss_g1038
	global_load_dwordx4 v[64:67], v[80:81], off offset:64
.Lss_g1038:
	s_cmp_lg_u32 s98, 1
	s_cbranch_scc1 .Lss_g1039
	global_load_dwordx4 v[52:55], v[80:81], off offset:2048
.Lss_g1039:
	s_cmp_lg_u32 s98, 1
	s_cbranch_scc1 .Lss_g1040
	global_load_dwordx4 v[48:51], v[80:81], off offset:2112
.Lss_g1040:
	s_cmp_lg_u32 s98, 1
	s_cbranch_scc1 .Lss_g1041
	global_load_dwordx4 v[44:47], v[82:83], off offset:-4096
.Lss_g1041:
	s_cmp_lg_u32 s98, 0
	s_cbranch_scc1 .Lss_g1042
	global_load_dwordx4 v[40:43], v[34:35], off offset:64
.Lss_g1042:
	s_cmp_lg_u32 s98, 0
	s_cbranch_scc1 .Lss_g1043
	global_load_dwordx4 v[36:39], v[32:33], off
.Lss_g1043:
	s_nop 0
	s_cmp_lg_u32 s98, 0
	s_cbranch_scc1 .Lss_g1044
	global_load_dwordx4 v[32:35], v[32:33], off offset:64
.Lss_g1044:
	s_nop 0
	s_cmp_lg_u32 s98, 3
	s_cbranch_scc1 .Lss_g1045
	global_load_dwordx4 v[92:95], v[82:83], off

.Lss_g1048:
	s_nop 0
	global_load_dwordx2 v[180:181], v223, s[10:11]
	global_load_dwordx2 v[172:173], v223, s[10:11] offset:512
	global_load_dwordx2 v[196:197], v223, s[10:11] offset:1024
	global_load_dwordx2 v[188:189], v223, s[10:11] offset:1536
	global_load_dwordx2 v[204:205], v[148:149], off
	global_load_dwordx2 v[200:201], v[150:151], off offset:512
	s_waitcnt vmcnt(22)
	s_cmp_lg_u32 s98, 0
	s_cbranch_scc1 .Lss_x1062_1
	ds_write_b128 v234, v[0:3] offset:45056
	ds_write_b128 v234, v[4:7] offset:46080
	ds_write_b128 v234, v[8:11] offset:47104
	s_branch .Lss_x1062_d

.Lss_x1062_2:
	s_cmp_lg_u32 s98, 2
	s_cbranch_scc1 .Lss_x1062_3
	ds_write_b128 v234, v[24:27] offset:51200
	ds_write_b128 v234, v[28:31] offset:52224
	ds_write_b128 v234, v[56:59] offset:53248
	s_branch .Lss_x1062_d
.Lss_x1062_3:
	ds_write_b128 v234, v[60:63] offset:54272
	ds_write_b128 v234, v[72:75] offset:55296
	ds_write_b128 v234, v[76:79] offset:56320
.Lss_x1062_d:
	s_waitcnt lgkmcnt(0)
	s_barrier
	ds_read_b128 v[0:3], v234 offset:45056
	ds_read_b128 v[4:7], v234 offset:46080
	ds_read_b128 v[8:11], v234 offset:47104
	ds_read_b128 v[12:15], v234 offset:48128
	ds_read_b128 v[16:19], v234 offset:49152
	ds_read_b128 v[20:23], v234 offset:50176
	ds_read_b128 v[24:27], v234 offset:51200
	ds_read_b128 v[28:31], v234 offset:52224
	ds_read_b128 v[56:59], v234 offset:53248
	ds_read_b128 v[60:63], v234 offset:54272
	ds_read_b128 v[72:75], v234 offset:55296
	ds_read_b128 v[76:79], v234 offset:56320
	s_waitcnt lgkmcnt(0)
	ds_write2_b32 v221, v160, v226 offset1:16
	ds_write2_b32 v221, v162, v228 offset0:136 offset1:152
	ds_write2_b32 v221, v230, v161 offset0:32 offset1:68
	ds_write2_b32 v221, v227, v231 offset0:84 offset1:100
	ds_write2_b32 v221, v232, v163 offset0:168 offset1:204
	ds_write2_b32 v221, v229, v233 offset0:220 offset1:236
	ds_write2_b32 v222, v144, v145 offset1:68
	ds_write2_b32 v222, v146, v147 offset0:136 offset1:204
	ds_read_b128 v[144:147], v224
	ds_read_b128 v[148:151], v224 offset:16
	s_min_u32 s10, s7, 27
	s_add_i32 s10, s6, s10
	s_mul_i32 s12, s10, 0x3000
	s_waitcnt lgkmcnt(1)
	v_cvt_pk_bf16_f32 v156, v144, v145
	v_lshlrev_b32_e32 v152, 16, v156
	v_and_b32_e32 v153, 0xffff0000, v156
	v_pk_add_f32 v[144:145], v[144:145], v[152:153] neg_lo:[0,1] neg_hi:[0,1]
	v_cvt_pk_bf16_f32 v157, v146, v147
	v_cvt_pk_bf16_f32 v160, v144, v145
	v_lshlrev_b32_e32 v144, 16, v157
	v_and_b32_e32 v145, 0xffff0000, v157
	v_pk_add_f32 v[144:145], v[146:147], v[144:145] neg_lo:[0,1] neg_hi:[0,1]
	s_waitcnt lgkmcnt(0)
	v_cvt_pk_bf16_f32 v158, v148, v149
	v_cvt_pk_bf16_f32 v161, v144, v145
	v_lshlrev_b32_e32 v144, 16, v158
	v_and_b32_e32 v145, 0xffff0000, v158
	v_pk_add_f32 v[144:145], v[148:149], v[144:145] neg_lo:[0,1] neg_hi:[0,1]
	v_cvt_pk_bf16_f32 v159, v150, v151
	v_cvt_pk_bf16_f32 v162, v144, v145
	v_lshlrev_b32_e32 v144, 16, v159
	v_and_b32_e32 v145, 0xffff0000, v159
	v_pk_add_f32 v[144:145], v[150:151], v[144:145] neg_lo:[0,1] neg_hi:[0,1]
	s_add_u32 s10, s80, s12
	v_cvt_pk_bf16_f32 v163, v144, v145
	ds_read_b128 v[144:147], v224 offset:128
	s_addc_u32 s11, s81, 0
	s_waitcnt lgkmcnt(0)
	v_cvt_pk_bf16_f32 v226, v144, v145
	v_lshlrev_b32_e32 v148, 16, v226
	v_and_b32_e32 v149, 0xffff0000, v226
	v_pk_add_f32 v[144:145], v[144:145], v[148:149] neg_lo:[0,1] neg_hi:[0,1]
	v_cvt_pk_bf16_f32 v227, v146, v147
	v_cvt_pk_bf16_f32 v230, v144, v145
	v_lshlrev_b32_e32 v144, 16, v227
	v_and_b32_e32 v145, 0xffff0000, v227
	v_pk_add_f32 v[144:145], v[146:147], v[144:145] neg_lo:[0,1] neg_hi:[0,1]
	s_nop 0
	v_cvt_pk_bf16_f32 v231, v144, v145
	ds_read_b128 v[144:147], v224 offset:144
	s_waitcnt lgkmcnt(0)
	v_cvt_pk_bf16_f32 v228, v144, v145
	v_lshlrev_b32_e32 v148, 16, v228
	v_and_b32_e32 v149, 0xffff0000, v228
	v_pk_add_f32 v[144:145], v[144:145], v[148:149] neg_lo:[0,1] neg_hi:[0,1]
	v_cvt_pk_bf16_f32 v229, v146, v147
	v_cvt_pk_bf16_f32 v232, v144, v145
	v_lshlrev_b32_e32 v144, 16, v229
	v_and_b32_e32 v145, 0xffff0000, v229
	v_pk_add_f32 v[144:145], v[146:147], v[144:145] neg_lo:[0,1] neg_hi:[0,1]
	v_lshlrev_b32_e32 v146, 16, v203
	v_cvt_pk_bf16_f32 v233, v144, v145
	v_lshlrev_b32_e32 v144, 16, v202
	v_and_b32_e32 v145, 0xffff0000, v202
	v_and_b32_e32 v147, 0xffff0000, v203
	s_nop 1
	v_mfma_f32_16x16x32_bf16 v[144:147], v[156:159], v[76:79], v[144:147]
	v_mfma_f32_16x16x32_bf16 v[76:79], v[160:163], v[76:79], v[144:147]
	v_mfma_f32_16x16x32_bf16 v[76:79], v[226:229], v[72:75], v[76:79]
	v_mfma_f32_16x16x32_bf16 v[72:75], v[230:233], v[72:75], v[76:79]
	s_nop 6
	v_lshlrev_b32_e32 v76, 16, v198
	v_and_b32_e32 v77, 0xffff0000, v198
	v_lshlrev_b32_e32 v78, 16, v199
	v_and_b32_e32 v79, 0xffff0000, v199
	s_nop 1
	v_mfma_f32_16x16x32_bf16 v[76:79], v[156:159], v[56:59], v[76:79]
	v_mfma_f32_16x16x32_bf16 v[56:59], v[160:163], v[56:59], v[76:79]
	v_mfma_f32_16x16x32_bf16 v[56:59], v[226:229], v[60:63], v[56:59]
	v_mfma_f32_16x16x32_bf16 v[56:59], v[230:233], v[60:63], v[56:59]
	v_lshlrev_b32_e32 v60, 16, v184
	v_and_b32_e32 v61, 0xffff0000, v184
	v_lshlrev_b32_e32 v62, 16, v185
	v_and_b32_e32 v63, 0xffff0000, v185
	s_nop 1
	v_mfma_f32_16x16x32_bf16 v[60:63], v[156:159], v[28:31], v[60:63]
	v_mfma_f32_16x16x32_bf16 v[28:31], v[160:163], v[28:31], v[60:63]
	v_mfma_f32_16x16x32_bf16 v[28:31], v[226:229], v[24:27], v[28:31]
	v_mfma_f32_16x16x32_bf16 v[144:147], v[230:233], v[24:27], v[28:31]
	v_lshlrev_b32_e32 v24, 16, v174
	v_and_b32_e32 v25, 0xffff0000, v174
	v_lshlrev_b32_e32 v26, 16, v175
	v_and_b32_e32 v27, 0xffff0000, v175
	s_nop 1
	v_mfma_f32_16x16x32_bf16 v[24:27], v[156:159], v[20:23], v[24:27]
	v_mfma_f32_16x16x32_bf16 v[20:23], v[160:163], v[20:23], v[24:27]
	v_mfma_f32_16x16x32_bf16 v[20:23], v[226:229], v[16:19], v[20:23]
	v_mfma_f32_16x16x32_bf16 v[148:151], v[230:233], v[16:19], v[20:23]
	v_lshlrev_b32_e32 v16, 16, v170
	v_and_b32_e32 v17, 0xffff0000, v170
	v_lshlrev_b32_e32 v18, 16, v171
	v_and_b32_e32 v19, 0xffff0000, v171
	s_nop 1
	v_mfma_f32_16x16x32_bf16 v[16:19], v[156:159], v[12:15], v[16:19]
	v_mfma_f32_16x16x32_bf16 v[12:15], v[160:163], v[12:15], v[16:19]
	v_mfma_f32_16x16x32_bf16 v[12:15], v[226:229], v[8:11], v[12:15]
	v_mfma_f32_16x16x32_bf16 v[152:155], v[230:233], v[8:11], v[12:15]
	v_lshlrev_b32_e32 v8, 16, v166
	v_and_b32_e32 v9, 0xffff0000, v166
	v_lshlrev_b32_e32 v10, 16, v167
	v_and_b32_e32 v11, 0xffff0000, v167
	s_nop 1
	v_mfma_f32_16x16x32_bf16 v[8:11], v[156:159], v[4:7], v[8:11]
	v_mfma_f32_16x16x32_bf16 v[4:7], v[160:163], v[4:7], v[8:11]
	v_mfma_f32_16x16x32_bf16 v[4:7], v[226:229], v[0:3], v[4:7]
	v_mfma_f32_16x16x32_bf16 v[156:159], v[230:233], v[0:3], v[4:7]
	v_lshl_add_u64 v[2:3], v[176:177], 0, v[164:165]
	v_cvt_pk_bf16_f32 v0, v72, v73
	v_cvt_pk_bf16_f32 v1, v74, v75
	s_nop 3
	v_add_co_u32_e32 v4, vcc, s8, v2
	s_nop 1
	v_addc_co_u32_e32 v5, vcc, 0, v3, vcc
	v_add_co_u32_e32 v2, vcc, s9, v2
	global_store_dwordx2 v[4:5], v[0:1], off
	v_cvt_pk_bf16_f32 v0, v56, v57
	v_cvt_pk_bf16_f32 v1, v58, v59
	v_addc_co_u32_e32 v3, vcc, 0, v3, vcc
	global_store_dwordx2 v[2:3], v[0:1], off
	v_lshl_add_u64 v[0:1], s[10:11], 0, v[186:187]
	v_lshl_add_u64 v[56:57], v[0:1], 0, v[190:191]
	v_add_co_u32_e32 v2, vcc, s5, v56
	v_lshl_add_u64 v[0:1], v[0:1], 0, v[192:193]
	s_nop 0
	v_addc_co_u32_e32 v3, vcc, 0, v57, vcc
	v_add_co_u32_e32 v58, vcc, s4, v56
	s_add_u32 s10, s16, s12
	s_addc_u32 s11, s17, 0
	s_nop 0
	v_addc_co_u32_e32 v59, vcc, 0, v57, vcc
	v_lshl_add_u64 v[60:61], v[56:57], 0, s[0:1]
	s_cmp_lg_u32 s98, 2
	s_cbranch_scc1 .Lss_g1049
	global_load_dwordx4 v[28:31], v[56:57], off
.Lss_g1049:
	s_cmp_lg_u32 s98, 2
	s_cbranch_scc1 .Lss_g1050
	global_load_dwordx4 v[24:27], v[56:57], off offset:64
.Lss_g1050:
	s_cmp_lg_u32 s98, 1
	s_cbranch_scc1 .Lss_g1051
	global_load_dwordx4 v[20:23], v[56:57], off offset:2048
.Lss_g1051:
	s_cmp_lg_u32 s98, 1
	s_cbranch_scc1 .Lss_g1052
	global_load_dwordx4 v[16:19], v[56:57], off offset:2112
.Lss_g1052:
	s_cmp_lg_u32 s98, 1
	s_cbranch_scc1 .Lss_g1053
	global_load_dwordx4 v[12:15], v[58:59], off offset:-4096

.Lss_g1054:
	s_cmp_lg_u32 s98, 0
	s_cbranch_scc1 .Lss_g1055
	global_load_dwordx4 v[4:7], v[0:1], off
.Lss_g1055:
	s_nop 0
	s_cmp_lg_u32 s98, 0
	s_cbranch_scc1 .Lss_g1056
	global_load_dwordx4 v[0:3], v[0:1], off offset:64
.Lss_g1056:
	s_cmp_lg_u32 s98, 3
	s_cbranch_scc1 .Lss_g1057
	global_load_dwordx4 v[76:79], v[58:59], off
.Lss_g1057:
	s_cmp_lg_u32 s98, 3
	s_cbranch_scc1 .Lss_g1058
	global_load_dwordx4 v[72:75], v[60:61], off offset:64
.Lss_g1058:
	s_nop 0
	s_cmp_lg_u32 s98, 2
	s_cbranch_scc1 .Lss_g1059
	global_load_dwordx4 v[56:59], v[60:61], off offset:2048
.Lss_g1059:
	s_nop 0
	s_cmp_lg_u32 s98, 3
	s_cbranch_scc1 .Lss_g1060
	global_load_dwordx4 v[60:63], v[60:61], off offset:2112
.Lss_g1060:
	s_nop 0
	global_load_dwordx2 v[184:185], v223, s[10:11]
	global_load_dwordx2 v[174:175], v223, s[10:11] offset:512
	global_load_dwordx2 v[170:171], v223, s[10:11] offset:1024
	global_load_dwordx2 v[166:167], v223, s[10:11] offset:1536
	v_lshl_add_u64 v[160:161], s[10:11], 0, v[194:195]
	v_lshl_add_u64 v[162:163], v[160:161], 0, s[0:1]
	v_add_co_u32_e32 v160, vcc, 0x2000, v160
	s_cmp_gt_u32 s7, 29
	s_nop 0
	v_addc_co_u32_e32 v161, vcc, 0, v161, vcc
	global_load_dwordx2 v[202:203], v[160:161], off
	global_load_dwordx2 v[198:199], v[162:163], off offset:512
	s_cbranch_scc1 .LBB0_735
	s_waitcnt vmcnt(22)
	s_cmp_lg_u32 s98, 0
	s_cbranch_scc1 .Lss_x1063_1
	ds_write_b128 v234, v[96:99] offset:20480
	ds_write_b128 v234, v[100:103] offset:21504
	ds_write_b128 v234, v[104:107] offset:22528
	s_branch .Lss_x1063_d
.Lss_x1063_1:
	s_cmp_lg_u32 s98, 1
	s_cbranch_scc1 .Lss_x1063_2
	ds_write_b128 v234, v[108:111] offset:23552
	ds_write_b128 v234, v[112:115] offset:24576
	ds_write_b128 v234, v[116:119] offset:25600
	s_branch .Lss_x1063_d
.Lss_x1063_2:
	s_cmp_lg_u32 s98, 2
	s_cbranch_scc1 .Lss_x1063_3
	ds_write_b128 v234, v[120:123] offset:26624
	ds_write_b128 v234, v[124:127] offset:27648
	ds_write_b128 v234, v[128:131] offset:28672
	s_branch .Lss_x1063_d
.Lss_x1063_3:
	ds_write_b128 v234, v[132:135] offset:29696
	ds_write_b128 v234, v[136:139] offset:30720
	ds_write_b128 v234, v[140:143] offset:31744
.Lss_x1063_d:
	s_waitcnt lgkmcnt(0)
	s_barrier
	ds_read_b128 v[96:99], v234 offset:20480
	ds_read_b128 v[100:103], v234 offset:21504
	ds_read_b128 v[104:107], v234 offset:22528
	ds_read_b128 v[108:111], v234 offset:23552
	ds_read_b128 v[112:115], v234 offset:24576
	ds_read_b128 v[116:119], v234 offset:25600
	ds_read_b128 v[120:123], v234 offset:26624
	ds_read_b128 v[124:127], v234 offset:27648
	ds_read_b128 v[128:131], v234 offset:28672
	ds_read_b128 v[132:135], v234 offset:29696
	ds_read_b128 v[136:139], v234 offset:30720
	ds_read_b128 v[140:143], v234 offset:31744
	s_waitcnt lgkmcnt(0)
	ds_write2_b32 v221, v144, v148 offset1:16
	ds_write2_b32 v221, v146, v150 offset0:136 offset1:152
	ds_write2_b32 v221, v152, v145 offset0:32 offset1:68
	ds_write2_b32 v221, v149, v153 offset0:84 offset1:100
	ds_write2_b32 v221, v154, v147 offset0:168 offset1:204
	ds_write2_b32 v221, v151, v155 offset0:220 offset1:236
	ds_write2_b32 v222, v156, v157 offset1:68
	ds_write2_b32 v222, v158, v159 offset0:136 offset1:204
	ds_read_b128 v[144:147], v224
	ds_read_b128 v[148:151], v224 offset:16
	s_waitcnt lgkmcnt(1)
	v_cvt_pk_bf16_f32 v156, v144, v145
	v_lshlrev_b32_e32 v152, 16, v156
	v_and_b32_e32 v153, 0xffff0000, v156
	v_pk_add_f32 v[144:145], v[144:145], v[152:153] neg_lo:[0,1] neg_hi:[0,1]
	v_cvt_pk_bf16_f32 v157, v146, v147
	v_cvt_pk_bf16_f32 v160, v144, v145
	v_lshlrev_b32_e32 v144, 16, v157
	v_and_b32_e32 v145, 0xffff0000, v157
	v_pk_add_f32 v[144:145], v[146:147], v[144:145] neg_lo:[0,1] neg_hi:[0,1]
	s_waitcnt lgkmcnt(0)
	v_cvt_pk_bf16_f32 v158, v148, v149
	v_cvt_pk_bf16_f32 v161, v144, v145
	v_lshlrev_b32_e32 v144, 16, v158
	v_and_b32_e32 v145, 0xffff0000, v158
	v_pk_add_f32 v[144:145], v[148:149], v[144:145] neg_lo:[0,1] neg_hi:[0,1]
	v_cvt_pk_bf16_f32 v159, v150, v151
	v_cvt_pk_bf16_f32 v162, v144, v145
	v_lshlrev_b32_e32 v144, 16, v159
	v_and_b32_e32 v145, 0xffff0000, v159
	v_pk_add_f32 v[144:145], v[150:151], v[144:145] neg_lo:[0,1] neg_hi:[0,1]
	s_nop 0
	v_cvt_pk_bf16_f32 v163, v144, v145
	ds_read_b128 v[144:147], v224 offset:128
	s_waitcnt lgkmcnt(0)
	v_cvt_pk_bf16_f32 v226, v144, v145
	v_lshlrev_b32_e32 v148, 16, v226
	v_and_b32_e32 v149, 0xffff0000, v226
	v_pk_add_f32 v[144:145], v[144:145], v[148:149] neg_lo:[0,1] neg_hi:[0,1]
	v_cvt_pk_bf16_f32 v227, v146, v147
	v_cvt_pk_bf16_f32 v230, v144, v145
	v_lshlrev_b32_e32 v144, 16, v227
	v_and_b32_e32 v145, 0xffff0000, v227
	v_pk_add_f32 v[144:145], v[146:147], v[144:145] neg_lo:[0,1] neg_hi:[0,1]
	s_nop 0
	v_cvt_pk_bf16_f32 v231, v144, v145
	ds_read_b128 v[144:147], v224 offset:144
	s_waitcnt lgkmcnt(0)
	v_cvt_pk_bf16_f32 v228, v144, v145
	v_lshlrev_b32_e32 v148, 16, v228
	v_and_b32_e32 v149, 0xffff0000, v228
	v_pk_add_f32 v[144:145], v[144:145], v[148:149] neg_lo:[0,1] neg_hi:[0,1]
	v_cvt_pk_bf16_f32 v229, v146, v147
	v_cvt_pk_bf16_f32 v232, v144, v145
	v_lshlrev_b32_e32 v144, 16, v229
	v_and_b32_e32 v145, 0xffff0000, v229
	v_pk_add_f32 v[144:145], v[146:147], v[144:145] neg_lo:[0,1] neg_hi:[0,1]
	s_waitcnt vmcnt(63)
	v_lshlrev_b32_e32 v146, 16, v217
	v_cvt_pk_bf16_f32 v233, v144, v145
	v_lshlrev_b32_e32 v144, 16, v216
	v_and_b32_e32 v145, 0xffff0000, v216
	v_and_b32_e32 v147, 0xffff0000, v217
	s_nop 1
	v_mfma_f32_16x16x32_bf16 v[144:147], v[156:159], v[140:143], v[144:147]
	v_mfma_f32_16x16x32_bf16 v[140:143], v[160:163], v[140:143], v[144:147]
	v_mfma_f32_16x16x32_bf16 v[140:143], v[226:229], v[136:139], v[140:143]
	v_mfma_f32_16x16x32_bf16 v[136:139], v[230:233], v[136:139], v[140:143]
	s_waitcnt vmcnt(63)
	s_nop 5
	v_lshlrev_b32_e32 v140, 16, v214
	v_and_b32_e32 v141, 0xffff0000, v214
	v_lshlrev_b32_e32 v142, 16, v215
	v_and_b32_e32 v143, 0xffff0000, v215
	s_nop 1
	v_mfma_f32_16x16x32_bf16 v[140:143], v[156:159], v[132:135], v[140:143]
	v_mfma_f32_16x16x32_bf16 v[132:135], v[160:163], v[132:135], v[140:143]
	v_mfma_f32_16x16x32_bf16 v[132:135], v[226:229], v[128:131], v[132:135]
	v_mfma_f32_16x16x32_bf16 v[128:131], v[230:233], v[128:131], v[132:135]
	s_nop 6
	v_lshlrev_b32_e32 v132, 16, v212
	v_and_b32_e32 v133, 0xffff0000, v212
	v_lshlrev_b32_e32 v134, 16, v213
	v_and_b32_e32 v135, 0xffff0000, v213
	s_nop 1
	v_mfma_f32_16x16x32_bf16 v[132:135], v[156:159], v[124:127], v[132:135]
	v_mfma_f32_16x16x32_bf16 v[124:127], v[160:163], v[124:127], v[132:135]
	v_mfma_f32_16x16x32_bf16 v[124:127], v[226:229], v[120:123], v[124:127]
	v_mfma_f32_16x16x32_bf16 v[144:147], v[230:233], v[120:123], v[124:127]
	v_lshlrev_b32_e32 v120, 16, v210
	v_and_b32_e32 v121, 0xffff0000, v210
	v_lshlrev_b32_e32 v122, 16, v211
	v_and_b32_e32 v123, 0xffff0000, v211
	s_nop 1
	v_mfma_f32_16x16x32_bf16 v[120:123], v[156:159], v[116:119], v[120:123]
	v_mfma_f32_16x16x32_bf16 v[116:119], v[160:163], v[116:119], v[120:123]
	v_mfma_f32_16x16x32_bf16 v[116:119], v[226:229], v[112:115], v[116:119]
	v_mfma_f32_16x16x32_bf16 v[148:151], v[230:233], v[112:115], v[116:119]
	v_lshlrev_b32_e32 v112, 16, v208
	v_and_b32_e32 v113, 0xffff0000, v208
	v_lshlrev_b32_e32 v114, 16, v209
	v_and_b32_e32 v115, 0xffff0000, v209
	s_nop 1
	v_mfma_f32_16x16x32_bf16 v[112:115], v[156:159], v[108:111], v[112:115]
	v_mfma_f32_16x16x32_bf16 v[108:111], v[160:163], v[108:111], v[112:115]
	v_mfma_f32_16x16x32_bf16 v[108:111], v[226:229], v[100:103], v[108:111]
	v_mfma_f32_16x16x32_bf16 v[152:155], v[230:233], v[100:103], v[108:111]
	v_lshlrev_b32_e32 v100, 16, v206
	v_and_b32_e32 v101, 0xffff0000, v206
	v_lshlrev_b32_e32 v102, 16, v207
	v_and_b32_e32 v103, 0xffff0000, v207
	s_nop 1
	v_mfma_f32_16x16x32_bf16 v[100:103], v[156:159], v[104:107], v[100:103]
	v_mfma_f32_16x16x32_bf16 v[100:103], v[160:163], v[104:107], v[100:103]
	v_mfma_f32_16x16x32_bf16 v[100:103], v[226:229], v[96:99], v[100:103]
	v_mfma_f32_16x16x32_bf16 v[156:159], v[230:233], v[96:99], v[100:103]
	v_lshl_add_u64 v[98:99], v[176:177], 0, v[182:183]
	v_cvt_pk_bf16_f32 v96, v136, v137
	v_cvt_pk_bf16_f32 v97, v138, v139
	s_nop 3
	v_add_co_u32_e32 v100, vcc, s8, v98
	s_nop 1
	v_addc_co_u32_e32 v101, vcc, 0, v99, vcc
	v_add_co_u32_e32 v98, vcc, s9, v98
	global_store_dwordx2 v[100:101], v[96:97], off
	v_cvt_pk_bf16_f32 v96, v128, v129
	v_cvt_pk_bf16_f32 v97, v130, v131
	v_addc_co_u32_e32 v99, vcc, 0, v99, vcc
	global_store_dwordx2 v[98:99], v[96:97], off
	s_branch .LBB0_735
.LBB0_738:
	s_lshl_b32 s0, s2, 14
	v_readlane_b32 s4, v243, 0
	s_waitcnt vmcnt(0)
	v_lshl_add_u32 v0, v220, 12, s0
	v_mov_b32_e32 v1, 0
	v_readlane_b32 s16, v243, 12
	v_readlane_b32 s17, v243, 13
	v_readlane_b32 s5, v243, 1
	v_readlane_b32 s6, v243, 2
	v_lshl_add_u64 v[2:3], s[16:17], 0, v[0:1]
	v_lshlrev_b32_e32 v0, 4, v219
	v_lshl_add_u64 v[0:1], v[2:3], 0, v[0:1]
	v_readlane_b32 s7, v243, 3
	v_readlane_b32 s8, v243, 4
	v_readlane_b32 s9, v243, 5
	v_readlane_b32 s10, v243, 6
	v_readlane_b32 s11, v243, 7
	v_readlane_b32 s12, v243, 8
	v_readlane_b32 s13, v243, 9
	v_readlane_b32 s14, v243, 10
	v_readlane_b32 s15, v243, 11
	v_readlane_b32 s18, v243, 14
	v_readlane_b32 s19, v243, 15
	global_store_dwordx4 v[0:1], v[144:147], off
	global_store_dwordx4 v[0:1], v[148:151], off offset:1024
	global_store_dwordx4 v[0:1], v[152:155], off offset:2048
	global_store_dwordx4 v[0:1], v[156:159], off offset:3072
	s_cmp_lt_i32 s93, 6
	s_cbranch_scc1 .LBB0_792

.LBB0_835:
	v_lshrrev_b32_e32 v234, 6, v218
	s_nop 1
	v_readfirstlane_b32 s98, v234
	v_and_b32_e32 v234, 63, v218
	v_lshlrev_b32_e32 v234, 4, v234
	v_readlane_b32 s4, v243, 0
	s_lshl_b32 s3, s2, 14
	v_readlane_b32 s10, v243, 6
	v_and_b32_e32 v113, 63, v218
	v_lshl_add_u32 v160, v214, 12, s3
	v_mov_b32_e32 v161, 0
	v_readlane_b32 s6, v243, 2
	v_readlane_b32 s8, v243, 4
	v_readlane_b32 s16, v243, 12
	v_readlane_b32 s17, v243, 13
	v_readlane_b32 s18, v243, 14
	v_readlane_b32 s19, v243, 15
	s_mul_i32 s10, s2, 0xc0000
	v_lshl_add_u64 v[0:1], s[16:17], 0, v[160:161]
	v_lshlrev_b32_e32 v160, 4, v113
	s_lshl_b32 s6, s2, 6
	s_add_i32 s8, s10, 0x63000
	v_readlane_b32 s16, v242, 1
	v_readlane_b32 s5, v243, 1
	v_lshl_add_u64 v[0:1], v[0:1], 0, v[160:161]
	v_lshl_or_b32 v120, v214, 7, v113
	v_readlane_b32 s17, v242, 2
	s_add_u32 s4, s16, s8
	v_readlane_b32 s7, v243, 3
	global_load_dwordx4 v[96:99], v[0:1], off
	global_load_dwordx4 v[100:103], v[0:1], off offset:1024
	global_load_dwordx4 v[104:107], v[0:1], off offset:2048
	global_load_dwordx4 v[108:111], v[0:1], off offset:3072
	v_lshlrev_b32_e32 v0, 6, v113
	s_addc_u32 s5, s17, 0
	v_lshlrev_b32_e32 v160, 3, v120
	v_readlane_b32 s9, v243, 5
	v_readlane_b32 s12, v243, 8
	v_and_b32_e32 v112, 0x3c0, v0
	v_lshrrev_b32_e32 v115, 1, v218
	v_or_b32_e32 v116, 0xc00, v0
	v_lshl_add_u64 v[0:1], s[4:5], 0, v[160:161]
	s_mov_b64 s[0:1], 0x2000
	s_movk_i32 s7, 0x2000
	s_add_u32 s8, s80, s8
	v_and_b32_e32 v114, 24, v115
	v_lshl_or_b32 v118, v214, 8, v113
	v_lshl_add_u64 v[2:3], v[0:1], 0, s[0:1]
	v_add_co_u32_e32 v0, vcc, s7, v0
	s_addc_u32 s9, s81, 0
	s_add_i32 s12, s10, 0x60000
	v_readlane_b32 s11, v243, 7
	v_addc_co_u32_e32 v1, vcc, 0, v1, vcc
	v_lshlrev_b32_e32 v46, 3, v118
	s_add_u32 s10, s16, s12
	v_lshlrev_b32_e32 v32, 1, v114
	v_mov_b32_e32 v33, v161
	s_addc_u32 s11, s17, 0
	global_load_dwordx2 v[162:163], v46, s[4:5] offset:1536
	global_load_dwordx2 v[166:167], v46, s[10:11] offset:512
	global_load_dwordx2 v[170:171], v46, s[10:11]
	global_load_dwordx2 v[164:165], v46, s[4:5] offset:1024
	global_load_dwordx2 v[184:185], v[2:3], off offset:512
	global_load_dwordx2 v[196:197], v[0:1], off
	global_load_dwordx2 v[168:169], v46, s[4:5] offset:512
	global_load_dwordx2 v[172:173], v46, s[4:5]
	v_lshlrev_b32_e32 v34, 1, v112
	v_mov_b32_e32 v35, v161
	v_lshl_add_u64 v[0:1], s[8:9], 0, v[32:33]
	v_lshl_add_u64 v[28:29], v[0:1], 0, v[34:35]
	v_add_co_u32_e32 v4, vcc, s7, v28
	s_movk_i32 s8, 0x1000
	s_nop 0
	v_addc_co_u32_e32 v5, vcc, 0, v29, vcc
	v_add_co_u32_e32 v12, vcc, s8, v28
	s_add_u32 s4, s80, s12
	s_nop 0
	v_addc_co_u32_e32 v13, vcc, 0, v29, vcc
	v_lshl_add_u64 v[38:39], s[10:11], 0, v[160:161]
	s_addc_u32 s5, s81, 0
	v_lshlrev_b32_e32 v36, 1, v116
	v_mov_b32_e32 v37, v161
	v_lshl_add_u64 v[44:45], v[38:39], 0, s[0:1]
	v_add_co_u32_e32 v38, vcc, s7, v38
	v_lshl_add_u64 v[32:33], s[4:5], 0, v[32:33]
	v_lshl_add_u64 v[2:3], v[28:29], 0, s[0:1]
	v_lshl_add_u64 v[0:1], v[0:1], 0, v[36:37]
	v_addc_co_u32_e32 v39, vcc, 0, v39, vcc
	s_waitcnt vmcnt(24)
	v_lshl_add_u64 v[72:73], v[32:33], 0, v[34:35]
	s_cmp_lg_u32 s98, 2
	s_cbranch_scc1 .Lss_g1
	global_load_dwordx4 v[40:43], v[2:3], off offset:2048
